# S5 chunk-carry scan inner loop hand-written: per-lane signed stride, 32 chunk-local states in flight per batch instead of 16, same fp32 operation order
# baseline (speedup 1.0000x reference)
; DI unsigned pk2(float x, float y) { f2_t v = {x, y}; bf2_t b = __builtin_convertvector(v, bf2_t); return __builtin_bit_cast(unsigned, b); }
;   DI float* sloc() const { return (float*)(ws + O_SLOC); }
;   DI float2* etab() const { return (float2*)(ws + O_ETAB); }
;   DI u16* carry() const { return (u16*)(ws + O_CARRY); }
; DI void carry_item(const Ctx& c, int layer, int it4) {
;     ...
;   const int dir = (tid >> 6) & 1, p = tid & 63;
;   const int nch = seq_len(b) >> 5, gc0 = b * 128;
;   const float2 lt = c.etab()[((size_t)((layer * 16 + g) * 2 + dir) * 64 + p) * 33 + 32];
;   const float* __restrict__ sl_base = c.sloc() + (size_t)g * 256 + dir * 128 + p * 2;
;   u16* __restrict__ ca_base = c.carry() + (size_t)g * 256 + dir * 128 + p * 2;
;   float cr = 0.f, ci = 0.f;
;   for (int k0 = 0; k0 < nch; k0 += 16) {
;     float2 sl[16];
; #pragma unroll
;     for (int u = 0; u < 16; ++u) {
;       const int ch = gc0 + (dir == 0 ? k0 + u : nch - 1 - (k0 + u));
;       sl[u] = *(const float2*)(sl_base + (size_t)ch * 4096);
;     }
; #pragma unroll
;     for (int u = 0; u < 16; ++u) {
;       const int ch = gc0 + (dir == 0 ? k0 + u : nch - 1 - (k0 + u));
;       *(unsigned*)(ca_base + (size_t)ch * 4096) = pk2(cr, ci);
;       const float nr = lt.x * cr - lt.y * ci + sl[u].x;
;       const float ni = lt.x * ci + lt.y * cr + sl[u].y;
;       cr = nr; ci = ni;
;     }
;   }
.LBB0_391:
	v_cndmask_b32_e32 v80, v12, v165, vcc
	v_add_u32_e32 v80, v80, v11
	v_lshlrev_b32_e32 v82, 14, v80
	v_mov_b32_e32 v83, 0
	v_lshl_add_u64 v[82:83], v[2:3], 0, v[82:83]
	v_lshlrev_b32_e32 v84, 13, v80
	v_mov_b32_e32 v85, 0
	v_lshl_add_u64 v[84:85], v[4:5], 0, v[84:85]
	v_mov_b32_e32 v90, 0x4000
	v_mov_b32_e32 v86, 0xffffc000
	v_cndmask_b32_e32 v86, v86, v90, vcc
	v_mov_b32_e32 v87, -1
	v_cndmask_b32_e32 v87, v87, v165, vcc
	v_mov_b32_e32 v90, 0x2000
	v_mov_b32_e32 v88, 0xffffe000
	v_cndmask_b32_e32 v88, v88, v90, vcc
	v_mov_b32_e32 v89, v87
	v_readfirstlane_b32 s6, v10
	s_lshr_b32 s6, s6, 5
.Lcarry_batch:
	global_load_dwordx2 v[100:101], v[82:83], off
	v_lshl_add_u64 v[82:83], v[82:83], 0, v[86:87]
	global_load_dwordx2 v[102:103], v[82:83], off
	v_lshl_add_u64 v[82:83], v[82:83], 0, v[86:87]
	global_load_dwordx2 v[104:105], v[82:83], off
	v_lshl_add_u64 v[82:83], v[82:83], 0, v[86:87]
	global_load_dwordx2 v[106:107], v[82:83], off
	v_lshl_add_u64 v[82:83], v[82:83], 0, v[86:87]
	global_load_dwordx2 v[108:109], v[82:83], off
	v_lshl_add_u64 v[82:83], v[82:83], 0, v[86:87]
	global_load_dwordx2 v[110:111], v[82:83], off
	v_lshl_add_u64 v[82:83], v[82:83], 0, v[86:87]
	global_load_dwordx2 v[112:113], v[82:83], off
	v_lshl_add_u64 v[82:83], v[82:83], 0, v[86:87]
	global_load_dwordx2 v[114:115], v[82:83], off
	v_lshl_add_u64 v[82:83], v[82:83], 0, v[86:87]
	global_load_dwordx2 v[116:117], v[82:83], off
	v_lshl_add_u64 v[82:83], v[82:83], 0, v[86:87]
	global_load_dwordx2 v[118:119], v[82:83], off
	v_lshl_add_u64 v[82:83], v[82:83], 0, v[86:87]
	global_load_dwordx2 v[120:121], v[82:83], off
	v_lshl_add_u64 v[82:83], v[82:83], 0, v[86:87]
	global_load_dwordx2 v[122:123], v[82:83], off
	v_lshl_add_u64 v[82:83], v[82:83], 0, v[86:87]
	global_load_dwordx2 v[124:125], v[82:83], off
	v_lshl_add_u64 v[82:83], v[82:83], 0, v[86:87]
	global_load_dwordx2 v[126:127], v[82:83], off
	v_lshl_add_u64 v[82:83], v[82:83], 0, v[86:87]
	global_load_dwordx2 v[128:129], v[82:83], off
	v_lshl_add_u64 v[82:83], v[82:83], 0, v[86:87]
	global_load_dwordx2 v[130:131], v[82:83], off
	v_lshl_add_u64 v[82:83], v[82:83], 0, v[86:87]
	global_load_dwordx2 v[132:133], v[82:83], off
	v_lshl_add_u64 v[82:83], v[82:83], 0, v[86:87]
	global_load_dwordx2 v[134:135], v[82:83], off
	v_lshl_add_u64 v[82:83], v[82:83], 0, v[86:87]
	global_load_dwordx2 v[136:137], v[82:83], off
	v_lshl_add_u64 v[82:83], v[82:83], 0, v[86:87]
	global_load_dwordx2 v[138:139], v[82:83], off
	v_lshl_add_u64 v[82:83], v[82:83], 0, v[86:87]
	global_load_dwordx2 v[140:141], v[82:83], off
	v_lshl_add_u64 v[82:83], v[82:83], 0, v[86:87]
	global_load_dwordx2 v[142:143], v[82:83], off
	v_lshl_add_u64 v[82:83], v[82:83], 0, v[86:87]
	global_load_dwordx2 v[144:145], v[82:83], off
	v_lshl_add_u64 v[82:83], v[82:83], 0, v[86:87]
	global_load_dwordx2 v[146:147], v[82:83], off
	v_lshl_add_u64 v[82:83], v[82:83], 0, v[86:87]
	global_load_dwordx2 v[148:149], v[82:83], off
	v_lshl_add_u64 v[82:83], v[82:83], 0, v[86:87]
	global_load_dwordx2 v[150:151], v[82:83], off
	v_lshl_add_u64 v[82:83], v[82:83], 0, v[86:87]
	global_load_dwordx2 v[152:153], v[82:83], off
	v_lshl_add_u64 v[82:83], v[82:83], 0, v[86:87]
	global_load_dwordx2 v[154:155], v[82:83], off
	v_lshl_add_u64 v[82:83], v[82:83], 0, v[86:87]
	global_load_dwordx2 v[156:157], v[82:83], off
	v_lshl_add_u64 v[82:83], v[82:83], 0, v[86:87]
	global_load_dwordx2 v[158:159], v[82:83], off
	v_lshl_add_u64 v[82:83], v[82:83], 0, v[86:87]
	global_load_dwordx2 v[160:161], v[82:83], off
	v_lshl_add_u64 v[82:83], v[82:83], 0, v[86:87]
	global_load_dwordx2 v[162:163], v[82:83], off
	v_lshl_add_u64 v[82:83], v[82:83], 0, v[86:87]
	s_waitcnt vmcnt(31)
	v_cvt_pk_bf16_f32 v94, v8, v9
	global_store_dword v[84:85], v94, off
	v_lshl_add_u64 v[84:85], v[84:85], 0, v[88:89]
	v_mul_f32_e32 v90, v1, v9
	v_mul_f32_e32 v91, v0, v9
	v_fma_f32 v92, v0, v8, -v90
	v_fma_f32 v93, v1, v8, v91
	v_add_f32_e32 v8, v100, v92
	v_add_f32_e32 v9, v101, v93
	s_waitcnt vmcnt(31)
	v_cvt_pk_bf16_f32 v95, v8, v9
	global_store_dword v[84:85], v95, off
	v_lshl_add_u64 v[84:85], v[84:85], 0, v[88:89]
	v_mul_f32_e32 v90, v1, v9
	v_mul_f32_e32 v91, v0, v9
	v_fma_f32 v92, v0, v8, -v90
	v_fma_f32 v93, v1, v8, v91
	v_add_f32_e32 v8, v102, v92
	v_add_f32_e32 v9, v103, v93
	s_waitcnt vmcnt(31)
	v_cvt_pk_bf16_f32 v94, v8, v9
	global_store_dword v[84:85], v94, off
	v_lshl_add_u64 v[84:85], v[84:85], 0, v[88:89]
	v_mul_f32_e32 v90, v1, v9
	v_mul_f32_e32 v91, v0, v9
	v_fma_f32 v92, v0, v8, -v90
	v_fma_f32 v93, v1, v8, v91
	v_add_f32_e32 v8, v104, v92
	v_add_f32_e32 v9, v105, v93
	s_waitcnt vmcnt(31)
	v_cvt_pk_bf16_f32 v95, v8, v9
	global_store_dword v[84:85], v95, off
	v_lshl_add_u64 v[84:85], v[84:85], 0, v[88:89]
	v_mul_f32_e32 v90, v1, v9
	v_mul_f32_e32 v91, v0, v9
	v_fma_f32 v92, v0, v8, -v90
	v_fma_f32 v93, v1, v8, v91
	v_add_f32_e32 v8, v106, v92
	v_add_f32_e32 v9, v107, v93
	s_waitcnt vmcnt(31)
	v_cvt_pk_bf16_f32 v94, v8, v9
	global_store_dword v[84:85], v94, off
	v_lshl_add_u64 v[84:85], v[84:85], 0, v[88:89]
	v_mul_f32_e32 v90, v1, v9
	v_mul_f32_e32 v91, v0, v9
	v_fma_f32 v92, v0, v8, -v90
	v_fma_f32 v93, v1, v8, v91
	v_add_f32_e32 v8, v108, v92
	v_add_f32_e32 v9, v109, v93
	s_waitcnt vmcnt(31)
	v_cvt_pk_bf16_f32 v95, v8, v9
	global_store_dword v[84:85], v95, off
	v_lshl_add_u64 v[84:85], v[84:85], 0, v[88:89]
	v_mul_f32_e32 v90, v1, v9
	v_mul_f32_e32 v91, v0, v9
	v_fma_f32 v92, v0, v8, -v90
	v_fma_f32 v93, v1, v8, v91
	v_add_f32_e32 v8, v110, v92
	v_add_f32_e32 v9, v111, v93
	s_waitcnt vmcnt(31)
; DI unsigned pk2(float x, float y) { f2_t v = {x, y}; bf2_t b = __builtin_convertvector(v, bf2_t); return __builtin_bit_cast(unsigned, b); }
; DI void carry_item(const Ctx& c, int layer, int it4) {
;     ...
; #pragma unroll
;     for (int u = 0; u < 16; ++u) {
;       const int ch = gc0 + (dir == 0 ? k0 + u : nch - 1 - (k0 + u));
;       *(unsigned*)(ca_base + (size_t)ch * 4096) = pk2(cr, ci);
;       const float nr = lt.x * cr - lt.y * ci + sl[u].x;
;       const float ni = lt.x * ci + lt.y * cr + sl[u].y;
;       cr = nr; ci = ni;
;     }
	v_cvt_pk_bf16_f32 v94, v8, v9
	global_store_dword v[84:85], v94, off
	v_lshl_add_u64 v[84:85], v[84:85], 0, v[88:89]
	v_mul_f32_e32 v90, v1, v9
	v_mul_f32_e32 v91, v0, v9
	v_fma_f32 v92, v0, v8, -v90
	v_fma_f32 v93, v1, v8, v91
	v_add_f32_e32 v8, v112, v92
	v_add_f32_e32 v9, v113, v93
	s_waitcnt vmcnt(31)
	v_cvt_pk_bf16_f32 v95, v8, v9
	global_store_dword v[84:85], v95, off
	v_lshl_add_u64 v[84:85], v[84:85], 0, v[88:89]
	v_mul_f32_e32 v90, v1, v9
	v_mul_f32_e32 v91, v0, v9
	v_fma_f32 v92, v0, v8, -v90
	v_fma_f32 v93, v1, v8, v91
	v_add_f32_e32 v8, v114, v92
	v_add_f32_e32 v9, v115, v93
	s_waitcnt vmcnt(31)
	v_cvt_pk_bf16_f32 v94, v8, v9
	global_store_dword v[84:85], v94, off
	v_lshl_add_u64 v[84:85], v[84:85], 0, v[88:89]
	v_mul_f32_e32 v90, v1, v9
	v_mul_f32_e32 v91, v0, v9
	v_fma_f32 v92, v0, v8, -v90
	v_fma_f32 v93, v1, v8, v91
	v_add_f32_e32 v8, v116, v92
	v_add_f32_e32 v9, v117, v93
	s_waitcnt vmcnt(31)
	v_cvt_pk_bf16_f32 v95, v8, v9
	global_store_dword v[84:85], v95, off
	v_lshl_add_u64 v[84:85], v[84:85], 0, v[88:89]
	v_mul_f32_e32 v90, v1, v9
	v_mul_f32_e32 v91, v0, v9
	v_fma_f32 v92, v0, v8, -v90
	v_fma_f32 v93, v1, v8, v91
	v_add_f32_e32 v8, v118, v92
	v_add_f32_e32 v9, v119, v93
	s_waitcnt vmcnt(31)
	v_cvt_pk_bf16_f32 v94, v8, v9
	global_store_dword v[84:85], v94, off
	v_lshl_add_u64 v[84:85], v[84:85], 0, v[88:89]
	v_mul_f32_e32 v90, v1, v9
	v_mul_f32_e32 v91, v0, v9
	v_fma_f32 v92, v0, v8, -v90
	v_fma_f32 v93, v1, v8, v91
	v_add_f32_e32 v8, v120, v92
	v_add_f32_e32 v9, v121, v93
	s_waitcnt vmcnt(31)
	v_cvt_pk_bf16_f32 v95, v8, v9
	global_store_dword v[84:85], v95, off
	v_lshl_add_u64 v[84:85], v[84:85], 0, v[88:89]
	v_mul_f32_e32 v90, v1, v9
	v_mul_f32_e32 v91, v0, v9
	v_fma_f32 v92, v0, v8, -v90
	v_fma_f32 v93, v1, v8, v91
	v_add_f32_e32 v8, v122, v92
	v_add_f32_e32 v9, v123, v93
	s_waitcnt vmcnt(31)
	v_cvt_pk_bf16_f32 v94, v8, v9
	global_store_dword v[84:85], v94, off
	v_lshl_add_u64 v[84:85], v[84:85], 0, v[88:89]
	v_mul_f32_e32 v90, v1, v9
	v_mul_f32_e32 v91, v0, v9
	v_fma_f32 v92, v0, v8, -v90
	v_fma_f32 v93, v1, v8, v91
	v_add_f32_e32 v8, v124, v92
	v_add_f32_e32 v9, v125, v93
	s_waitcnt vmcnt(31)
	v_cvt_pk_bf16_f32 v95, v8, v9
	global_store_dword v[84:85], v95, off
	v_lshl_add_u64 v[84:85], v[84:85], 0, v[88:89]
	v_mul_f32_e32 v90, v1, v9
	v_mul_f32_e32 v91, v0, v9
	v_fma_f32 v92, v0, v8, -v90
	v_fma_f32 v93, v1, v8, v91
	v_add_f32_e32 v8, v126, v92
	v_add_f32_e32 v9, v127, v93
	s_waitcnt vmcnt(31)
	v_cvt_pk_bf16_f32 v94, v8, v9
	global_store_dword v[84:85], v94, off
	v_lshl_add_u64 v[84:85], v[84:85], 0, v[88:89]
	v_mul_f32_e32 v90, v1, v9
	v_mul_f32_e32 v91, v0, v9
	v_fma_f32 v92, v0, v8, -v90
	v_fma_f32 v93, v1, v8, v91
	v_add_f32_e32 v8, v128, v92
	v_add_f32_e32 v9, v129, v93
	s_waitcnt vmcnt(31)
	v_cvt_pk_bf16_f32 v95, v8, v9
	global_store_dword v[84:85], v95, off
	v_lshl_add_u64 v[84:85], v[84:85], 0, v[88:89]
	v_mul_f32_e32 v90, v1, v9
	v_mul_f32_e32 v91, v0, v9
	v_fma_f32 v92, v0, v8, -v90
	v_fma_f32 v93, v1, v8, v91
	v_add_f32_e32 v8, v130, v92
	v_add_f32_e32 v9, v131, v93
	s_waitcnt vmcnt(31)
	v_cvt_pk_bf16_f32 v94, v8, v9
	global_store_dword v[84:85], v94, off
	v_lshl_add_u64 v[84:85], v[84:85], 0, v[88:89]
	v_mul_f32_e32 v90, v1, v9
	v_mul_f32_e32 v91, v0, v9
	v_fma_f32 v92, v0, v8, -v90
	v_fma_f32 v93, v1, v8, v91
	v_add_f32_e32 v8, v132, v92
	v_add_f32_e32 v9, v133, v93
	s_waitcnt vmcnt(31)
	v_cvt_pk_bf16_f32 v95, v8, v9
	global_store_dword v[84:85], v95, off
	v_lshl_add_u64 v[84:85], v[84:85], 0, v[88:89]
	v_mul_f32_e32 v90, v1, v9
	v_mul_f32_e32 v91, v0, v9
	v_fma_f32 v92, v0, v8, -v90
	v_fma_f32 v93, v1, v8, v91
	v_add_f32_e32 v8, v134, v92
	v_add_f32_e32 v9, v135, v93
	s_waitcnt vmcnt(31)
	v_cvt_pk_bf16_f32 v94, v8, v9
	global_store_dword v[84:85], v94, off
	v_lshl_add_u64 v[84:85], v[84:85], 0, v[88:89]
	v_mul_f32_e32 v90, v1, v9
	v_mul_f32_e32 v91, v0, v9
	v_fma_f32 v92, v0, v8, -v90
	v_fma_f32 v93, v1, v8, v91
	v_add_f32_e32 v8, v136, v92
	v_add_f32_e32 v9, v137, v93
	s_waitcnt vmcnt(31)
; DI unsigned pk2(float x, float y) { f2_t v = {x, y}; bf2_t b = __builtin_convertvector(v, bf2_t); return __builtin_bit_cast(unsigned, b); }
; DI void carry_item(const Ctx& c, int layer, int it4) {
;     ...
;   for (int k0 = 0; k0 < nch; k0 += 16) {
;     float2 sl[16];
; #pragma unroll
;     for (int u = 0; u < 16; ++u) {
;       const int ch = gc0 + (dir == 0 ? k0 + u : nch - 1 - (k0 + u));
;       sl[u] = *(const float2*)(sl_base + (size_t)ch * 4096);
;     }
; #pragma unroll
;     for (int u = 0; u < 16; ++u) {
;       const int ch = gc0 + (dir == 0 ? k0 + u : nch - 1 - (k0 + u));
;       *(unsigned*)(ca_base + (size_t)ch * 4096) = pk2(cr, ci);
;       const float nr = lt.x * cr - lt.y * ci + sl[u].x;
;       const float ni = lt.x * ci + lt.y * cr + sl[u].y;
;       cr = nr; ci = ni;
;     }
;   }
	v_cvt_pk_bf16_f32 v95, v8, v9
	global_store_dword v[84:85], v95, off
	v_lshl_add_u64 v[84:85], v[84:85], 0, v[88:89]
	v_mul_f32_e32 v90, v1, v9
	v_mul_f32_e32 v91, v0, v9
	v_fma_f32 v92, v0, v8, -v90
	v_fma_f32 v93, v1, v8, v91
	v_add_f32_e32 v8, v138, v92
	v_add_f32_e32 v9, v139, v93
	s_waitcnt vmcnt(31)
	v_cvt_pk_bf16_f32 v94, v8, v9
	global_store_dword v[84:85], v94, off
	v_lshl_add_u64 v[84:85], v[84:85], 0, v[88:89]
	v_mul_f32_e32 v90, v1, v9
	v_mul_f32_e32 v91, v0, v9
	v_fma_f32 v92, v0, v8, -v90
	v_fma_f32 v93, v1, v8, v91
	v_add_f32_e32 v8, v140, v92
	v_add_f32_e32 v9, v141, v93
	s_waitcnt vmcnt(31)
	v_cvt_pk_bf16_f32 v95, v8, v9
	global_store_dword v[84:85], v95, off
	v_lshl_add_u64 v[84:85], v[84:85], 0, v[88:89]
	v_mul_f32_e32 v90, v1, v9
	v_mul_f32_e32 v91, v0, v9
	v_fma_f32 v92, v0, v8, -v90
	v_fma_f32 v93, v1, v8, v91
	v_add_f32_e32 v8, v142, v92
	v_add_f32_e32 v9, v143, v93
	s_waitcnt vmcnt(31)
	v_cvt_pk_bf16_f32 v94, v8, v9
	global_store_dword v[84:85], v94, off
	v_lshl_add_u64 v[84:85], v[84:85], 0, v[88:89]
	v_mul_f32_e32 v90, v1, v9
	v_mul_f32_e32 v91, v0, v9
	v_fma_f32 v92, v0, v8, -v90
	v_fma_f32 v93, v1, v8, v91
	v_add_f32_e32 v8, v144, v92
	v_add_f32_e32 v9, v145, v93
	s_waitcnt vmcnt(31)
	v_cvt_pk_bf16_f32 v95, v8, v9
	global_store_dword v[84:85], v95, off
	v_lshl_add_u64 v[84:85], v[84:85], 0, v[88:89]
	v_mul_f32_e32 v90, v1, v9
	v_mul_f32_e32 v91, v0, v9
	v_fma_f32 v92, v0, v8, -v90
	v_fma_f32 v93, v1, v8, v91
	v_add_f32_e32 v8, v146, v92
	v_add_f32_e32 v9, v147, v93
	s_waitcnt vmcnt(31)
	v_cvt_pk_bf16_f32 v94, v8, v9
	global_store_dword v[84:85], v94, off
	v_lshl_add_u64 v[84:85], v[84:85], 0, v[88:89]
	v_mul_f32_e32 v90, v1, v9
	v_mul_f32_e32 v91, v0, v9
	v_fma_f32 v92, v0, v8, -v90
	v_fma_f32 v93, v1, v8, v91
	v_add_f32_e32 v8, v148, v92
	v_add_f32_e32 v9, v149, v93
	s_waitcnt vmcnt(31)
	v_cvt_pk_bf16_f32 v95, v8, v9
	global_store_dword v[84:85], v95, off
	v_lshl_add_u64 v[84:85], v[84:85], 0, v[88:89]
	v_mul_f32_e32 v90, v1, v9
	v_mul_f32_e32 v91, v0, v9
	v_fma_f32 v92, v0, v8, -v90
	v_fma_f32 v93, v1, v8, v91
	v_add_f32_e32 v8, v150, v92
	v_add_f32_e32 v9, v151, v93
	s_waitcnt vmcnt(31)
	v_cvt_pk_bf16_f32 v94, v8, v9
	global_store_dword v[84:85], v94, off
	v_lshl_add_u64 v[84:85], v[84:85], 0, v[88:89]
	v_mul_f32_e32 v90, v1, v9
	v_mul_f32_e32 v91, v0, v9
	v_fma_f32 v92, v0, v8, -v90
	v_fma_f32 v93, v1, v8, v91
	v_add_f32_e32 v8, v152, v92
	v_add_f32_e32 v9, v153, v93
	s_waitcnt vmcnt(31)
	v_cvt_pk_bf16_f32 v95, v8, v9
	global_store_dword v[84:85], v95, off
	v_lshl_add_u64 v[84:85], v[84:85], 0, v[88:89]
	v_mul_f32_e32 v90, v1, v9
	v_mul_f32_e32 v91, v0, v9
	v_fma_f32 v92, v0, v8, -v90
	v_fma_f32 v93, v1, v8, v91
	v_add_f32_e32 v8, v154, v92
	v_add_f32_e32 v9, v155, v93
	s_waitcnt vmcnt(31)
	v_cvt_pk_bf16_f32 v94, v8, v9
	global_store_dword v[84:85], v94, off
	v_lshl_add_u64 v[84:85], v[84:85], 0, v[88:89]
	v_mul_f32_e32 v90, v1, v9
	v_mul_f32_e32 v91, v0, v9
	v_fma_f32 v92, v0, v8, -v90
	v_fma_f32 v93, v1, v8, v91
	v_add_f32_e32 v8, v156, v92
	v_add_f32_e32 v9, v157, v93
	s_waitcnt vmcnt(31)
	v_cvt_pk_bf16_f32 v95, v8, v9
	global_store_dword v[84:85], v95, off
	v_lshl_add_u64 v[84:85], v[84:85], 0, v[88:89]
	v_mul_f32_e32 v90, v1, v9
	v_mul_f32_e32 v91, v0, v9
	v_fma_f32 v92, v0, v8, -v90
	v_fma_f32 v93, v1, v8, v91
	v_add_f32_e32 v8, v158, v92
	v_add_f32_e32 v9, v159, v93
	s_waitcnt vmcnt(31)
	v_cvt_pk_bf16_f32 v94, v8, v9
	global_store_dword v[84:85], v94, off
	v_lshl_add_u64 v[84:85], v[84:85], 0, v[88:89]
	v_mul_f32_e32 v90, v1, v9
	v_mul_f32_e32 v91, v0, v9
	v_fma_f32 v92, v0, v8, -v90
	v_fma_f32 v93, v1, v8, v91
	v_add_f32_e32 v8, v160, v92
	v_add_f32_e32 v9, v161, v93
	s_waitcnt vmcnt(31)
	v_cvt_pk_bf16_f32 v95, v8, v9
	global_store_dword v[84:85], v95, off
	v_lshl_add_u64 v[84:85], v[84:85], 0, v[88:89]
	v_mul_f32_e32 v90, v1, v9
	v_mul_f32_e32 v91, v0, v9
	v_fma_f32 v92, v0, v8, -v90
	v_fma_f32 v93, v1, v8, v91
	v_add_f32_e32 v8, v162, v92
	v_add_f32_e32 v9, v163, v93
	s_add_i32 s6, s6, -1
	s_cmp_lg_u32 s6, 0
	s_cbranch_scc1 .Lcarry_batch
	s_or_b64 exec, exec, s[2:3]
	v_readlane_b32 s0, v251, 52
	v_readlane_b32 s1, v251, 53
	s_load_dword s0, s[0:1], 0x0
	s_waitcnt lgkmcnt(0)
	s_add_i32 s5, s0, s5
	s_cmp_gt_i32 s5, 35
	s_cbranch_scc0 .LBB0_390
